# rwkv scan producer y write-back: eight LDS reads issued together, stores with scalar row base instead of 64-bit VALU adds
# speedup vs baseline: 1.0012x; 1.0012x over previous
; #define LAS __attribute__((address_space(3)))
; __device__ __forceinline__ bf16_t f2bf(float f) { return (bf16_t)(pk2(f, 0.f) & 0xffffu); }
; __device__ __forceinline__ void rwkv_store_chunk(const LAS float* L, int n, int pw, int lane, int b, int col, bf16_t* YR, int half) {
;     const LAS float* sY = L + 24576 + (n & 1) * 2048;
; #pragma unroll
;     for (int i = 0; i < 8; ++i) { const int tt = pw + 4 * i, m = b * T_ + 32 * n + tt; if ((lane >> 4) == half) YR[(size_t)m * 2048 + 1536 + col] = f2bf(sY[tt * 64 + lane]); }
; }
.LBB0_103:
	s_cmp_lg_u32 s72, 0
	s_cselect_b64 s[2:3], -1, 0
	s_and_b64 s[18:19], s[2:3], s[8:9]
	s_and_saveexec_b64 s[2:3], s[18:19]
	s_cbranch_execz .LBB0_98
	s_and_b32 s11, s46, 0x800
	v_lshl_add_u32 v63, s11, 2, v57
	v_add_u32_e32 v64, s21, v63
	v_add_u32_e32 v65, s24, v63
	v_add_u32_e32 v66, s26, v63
	v_add_u32_e32 v67, s29, v63
	v_add_u32_e32 v68, s34, v63
	v_add_u32_e32 v69, s40, v63
	v_add_u32_e32 v70, s42, v63
	v_add_u32_e32 v63, s45, v63
	ds_read_b32 v64, v64
	ds_read_b32 v65, v65
	ds_read_b32 v66, v66
	ds_read_b32 v67, v67
	ds_read_b32 v68, v68
	ds_read_b32 v69, v69
	ds_read_b32 v70, v70
	ds_read_b32 v63, v63
	s_add_i32 s11, s59, s72
	s_sub_i32 s18, s11, 36
	s_ashr_i32 s19, s18, 31
	s_lshl_b64 s[18:19], s[18:19], 12
	s_add_u32 s18, s12, s18
	s_addc_u32 s19, s13, s19
	s_waitcnt lgkmcnt(0)
	v_cvt_pk_bf16_f32 v64, v64, s0
	v_cvt_pk_bf16_f32 v65, v65, s0
	v_cvt_pk_bf16_f32 v66, v66, s0
	v_cvt_pk_bf16_f32 v67, v67, s0
	v_cvt_pk_bf16_f32 v68, v68, s0
	v_cvt_pk_bf16_f32 v69, v69, s0
	v_cvt_pk_bf16_f32 v70, v70, s0
	v_cvt_pk_bf16_f32 v63, v63, s0
	global_store_short v2, v64, s[18:19] offset:3072
	s_add_u32 s18, s18, 0x4000
	s_addc_u32 s19, s19, 0
	global_store_short v2, v65, s[18:19] offset:3072
	s_add_u32 s18, s18, 0x4000
	s_addc_u32 s19, s19, 0
	global_store_short v2, v66, s[18:19] offset:3072
	s_add_u32 s18, s18, 0x4000
	s_addc_u32 s19, s19, 0
	global_store_short v2, v67, s[18:19] offset:3072
	s_add_u32 s18, s18, 0x4000
	s_addc_u32 s19, s19, 0
	global_store_short v2, v68, s[18:19] offset:3072
	s_add_u32 s18, s18, 0x4000
	s_addc_u32 s19, s19, 0
	global_store_short v2, v69, s[18:19] offset:3072
	s_add_u32 s18, s18, 0x4000
	s_addc_u32 s19, s19, 0
	global_store_short v2, v70, s[18:19] offset:3072
	s_add_u32 s18, s18, 0x4000
	s_addc_u32 s19, s19, 0
	global_store_short v2, v63, s[18:19] offset:3072
	s_branch .LBB0_98
